# v6: P1 modulation loop: mod vectors loaded once, 2-row steps unrolled with double-buffered x loads and counted vmcnt
# baseline (speedup 1.0000x reference)
.LBB0_323:
	s_add_i32 s14, s10, s11
	s_add_i32 s15, s14, 2
	s_ashr_i32 s14, s15, 31
	s_lshr_b32 s14, s14, 20
	s_add_i32 s15, s15, s14
	s_ashr_i32 s14, s15, 12
	s_mul_hi_i32 s15, s14, 0x9000
	s_mul_i32 s14, s14, 0x9000
	s_add_u32 s14, s16, s14
	s_addc_u32 s15, s17, s15
	v_lshl_add_u64 v[48:49], s[14:15], 0, v[12:13]
	v_lshl_add_u64 v[48:49], v[48:49], 0, s[8:9]
	global_load_dwordx4 v[100:103], v[48:49], off
	global_load_dwordx4 v[104:107], v[48:49], off offset:1024
	global_load_dwordx4 v[108:111], v[48:49], off offset:2048
	global_load_dwordx4 v[112:115], v[48:49], off offset:3072
	global_load_dwordx4 v[116:119], v12, s[14:15]
	global_load_dwordx4 v[120:123], v12, s[14:15] offset:1024
	global_load_dwordx4 v[124:127], v12, s[14:15] offset:2048
	global_load_dwordx4 v[128:131], v12, s[14:15] offset:3072
	global_load_dwordx4 v[16:19], v[14:15], off offset:-4096
	global_load_dwordx4 v[20:23], v[14:15], off offset:-3072
	global_load_dwordx4 v[24:27], v[14:15], off offset:-2048
	global_load_dwordx4 v[28:31], v[14:15], off offset:-1024
	global_load_dwordx4 v[32:35], v[14:15], off
	global_load_dwordx4 v[36:39], v[14:15], off offset:1024
	global_load_dwordx4 v[40:43], v[14:15], off offset:2048
	global_load_dwordx4 v[44:47], v[14:15], off offset:3072
	v_lshl_add_u64 v[14:15], v[14:15], 0, s[12:13]
	s_waitcnt vmcnt(8)
	v_pk_add_f32 v[102:103], v[102:103], 1.0 op_sel_hi:[1,0]
	v_pk_add_f32 v[100:101], v[100:101], 1.0 op_sel_hi:[1,0]
	v_pk_add_f32 v[106:107], v[106:107], 1.0 op_sel_hi:[1,0]
	v_pk_add_f32 v[104:105], v[104:105], 1.0 op_sel_hi:[1,0]
	v_pk_add_f32 v[110:111], v[110:111], 1.0 op_sel_hi:[1,0]
	v_pk_add_f32 v[108:109], v[108:109], 1.0 op_sel_hi:[1,0]
	v_pk_add_f32 v[114:115], v[114:115], 1.0 op_sel_hi:[1,0]
	v_pk_add_f32 v[112:113], v[112:113], 1.0 op_sel_hi:[1,0]
	global_load_dwordx4 v[60:63], v[14:15], off offset:-4096
	global_load_dwordx4 v[64:67], v[14:15], off offset:-3072
	global_load_dwordx4 v[68:71], v[14:15], off offset:-2048
	global_load_dwordx4 v[72:75], v[14:15], off offset:-1024
	global_load_dwordx4 v[76:79], v[14:15], off
	global_load_dwordx4 v[80:83], v[14:15], off offset:1024
	global_load_dwordx4 v[84:87], v[14:15], off offset:2048
	global_load_dwordx4 v[88:91], v[14:15], off offset:3072
	v_lshl_add_u64 v[14:15], v[14:15], 0, s[12:13]
	s_waitcnt vmcnt(8)
	v_pk_fma_f32 v[18:19], v[18:19], v[102:103], v[118:119]
	v_pk_fma_f32 v[16:17], v[16:17], v[100:101], v[116:117]
	v_bfe_u32 v92, v16, 16, 1
	v_bfe_u32 v93, v17, 16, 1
	v_bfe_u32 v94, v18, 16, 1
	v_bfe_u32 v95, v19, 16, 1
	v_add3_u32 v16, v16, v92, s19
	v_add3_u32 v17, v17, v93, s19
	v_add3_u32 v18, v18, v94, s19
	v_add3_u32 v19, v19, v95, s19
	v_lshrrev_b32_e32 v16, 16, v16
	v_lshrrev_b32_e32 v18, 16, v18
	v_and_or_b32 v16, v17, s20, v16
	v_and_or_b32 v17, v19, s20, v18
	global_store_dwordx2 v1, v[16:17], s[0:1]
	v_pk_fma_f32 v[22:23], v[22:23], v[106:107], v[122:123]
	v_pk_fma_f32 v[20:21], v[20:21], v[104:105], v[120:121]
	v_bfe_u32 v92, v20, 16, 1
	v_bfe_u32 v93, v21, 16, 1
	v_bfe_u32 v94, v22, 16, 1
	v_bfe_u32 v95, v23, 16, 1
	v_add3_u32 v20, v20, v92, s19
	v_add3_u32 v21, v21, v93, s19
	v_add3_u32 v22, v22, v94, s19
	v_add3_u32 v23, v23, v95, s19
	v_lshrrev_b32_e32 v20, 16, v20
	v_lshrrev_b32_e32 v22, 16, v22
	v_and_or_b32 v20, v21, s20, v20
	v_and_or_b32 v21, v23, s20, v22
	global_store_dwordx2 v1, v[20:21], s[0:1] offset:512
	v_pk_fma_f32 v[26:27], v[26:27], v[110:111], v[126:127]
	v_pk_fma_f32 v[24:25], v[24:25], v[108:109], v[124:125]
	v_bfe_u32 v92, v24, 16, 1
	v_bfe_u32 v93, v25, 16, 1
	v_bfe_u32 v94, v26, 16, 1
	v_bfe_u32 v95, v27, 16, 1
	v_add3_u32 v24, v24, v92, s19
	v_add3_u32 v25, v25, v93, s19
	v_add3_u32 v26, v26, v94, s19
	v_add3_u32 v27, v27, v95, s19
	v_lshrrev_b32_e32 v24, 16, v24
	v_lshrrev_b32_e32 v26, 16, v26
	v_and_or_b32 v24, v25, s20, v24
	v_and_or_b32 v25, v27, s20, v26
	global_store_dwordx2 v1, v[24:25], s[0:1] offset:1024
	v_pk_fma_f32 v[30:31], v[30:31], v[114:115], v[130:131]
	v_pk_fma_f32 v[28:29], v[28:29], v[112:113], v[128:129]
	v_bfe_u32 v92, v28, 16, 1
	v_bfe_u32 v93, v29, 16, 1
	v_bfe_u32 v94, v30, 16, 1
	v_bfe_u32 v95, v31, 16, 1
	v_add3_u32 v28, v28, v92, s19
	v_add3_u32 v29, v29, v93, s19
	v_add3_u32 v30, v30, v94, s19
	v_add3_u32 v31, v31, v95, s19
	v_lshrrev_b32_e32 v28, 16, v28
	v_lshrrev_b32_e32 v30, 16, v30
	v_and_or_b32 v28, v29, s20, v28
	v_and_or_b32 v29, v31, s20, v30
	global_store_dwordx2 v1, v[28:29], s[0:1] offset:1536
	v_pk_fma_f32 v[34:35], v[34:35], v[102:103], v[118:119]
	v_pk_fma_f32 v[32:33], v[32:33], v[100:101], v[116:117]
	v_bfe_u32 v92, v32, 16, 1
	v_bfe_u32 v93, v33, 16, 1
	v_bfe_u32 v94, v34, 16, 1
	v_bfe_u32 v95, v35, 16, 1
	v_add3_u32 v32, v32, v92, s19
	v_add3_u32 v33, v33, v93, s19
	v_add3_u32 v34, v34, v94, s19
	v_add3_u32 v35, v35, v95, s19
	v_lshrrev_b32_e32 v32, 16, v32
	v_lshrrev_b32_e32 v34, 16, v34
	v_and_or_b32 v32, v33, s20, v32
	v_and_or_b32 v33, v35, s20, v34
	global_store_dwordx2 v1, v[32:33], s[0:1] offset:2048
	v_pk_fma_f32 v[38:39], v[38:39], v[106:107], v[122:123]
	v_pk_fma_f32 v[36:37], v[36:37], v[104:105], v[120:121]
	v_bfe_u32 v92, v36, 16, 1
	v_bfe_u32 v93, v37, 16, 1
	v_bfe_u32 v94, v38, 16, 1
	v_bfe_u32 v95, v39, 16, 1
	v_add3_u32 v36, v36, v92, s19
	v_add3_u32 v37, v37, v93, s19
	v_add3_u32 v38, v38, v94, s19
	v_add3_u32 v39, v39, v95, s19
	v_lshrrev_b32_e32 v36, 16, v36
	v_lshrrev_b32_e32 v38, 16, v38
	v_and_or_b32 v36, v37, s20, v36
	v_and_or_b32 v37, v39, s20, v38
	global_store_dwordx2 v1, v[36:37], s[0:1] offset:2560
	v_pk_fma_f32 v[42:43], v[42:43], v[110:111], v[126:127]
	v_pk_fma_f32 v[40:41], v[40:41], v[108:109], v[124:125]
	v_bfe_u32 v92, v40, 16, 1
	v_bfe_u32 v93, v41, 16, 1
	v_bfe_u32 v94, v42, 16, 1
	v_bfe_u32 v95, v43, 16, 1
	v_add3_u32 v40, v40, v92, s19
	v_add3_u32 v41, v41, v93, s19
	v_add3_u32 v42, v42, v94, s19
	v_add3_u32 v43, v43, v95, s19
	v_lshrrev_b32_e32 v40, 16, v40
	v_lshrrev_b32_e32 v42, 16, v42
	v_and_or_b32 v40, v41, s20, v40
	v_and_or_b32 v41, v43, s20, v42
	global_store_dwordx2 v1, v[40:41], s[0:1] offset:3072
	v_pk_fma_f32 v[46:47], v[46:47], v[114:115], v[130:131]
	v_pk_fma_f32 v[44:45], v[44:45], v[112:113], v[128:129]
	v_bfe_u32 v92, v44, 16, 1
	v_bfe_u32 v93, v45, 16, 1
	v_bfe_u32 v94, v46, 16, 1
	v_bfe_u32 v95, v47, 16, 1
	v_add3_u32 v44, v44, v92, s19
	v_add3_u32 v45, v45, v93, s19
	v_add3_u32 v46, v46, v94, s19
	v_add3_u32 v47, v47, v95, s19
	v_lshrrev_b32_e32 v44, 16, v44
	v_lshrrev_b32_e32 v46, 16, v46
	v_and_or_b32 v44, v45, s20, v44
	v_and_or_b32 v45, v47, s20, v46
	global_store_dwordx2 v1, v[44:45], s[0:1] offset:3584
	s_add_u32 s0, s0, 0x1000
	s_addc_u32 s1, s1, 0
	global_load_dwordx4 v[16:19], v[14:15], off offset:-4096
	global_load_dwordx4 v[20:23], v[14:15], off offset:-3072
	global_load_dwordx4 v[24:27], v[14:15], off offset:-2048
	global_load_dwordx4 v[28:31], v[14:15], off offset:-1024
	global_load_dwordx4 v[32:35], v[14:15], off
	global_load_dwordx4 v[36:39], v[14:15], off offset:1024
	global_load_dwordx4 v[40:43], v[14:15], off offset:2048
	global_load_dwordx4 v[44:47], v[14:15], off offset:3072
	v_lshl_add_u64 v[14:15], v[14:15], 0, s[12:13]
	s_waitcnt vmcnt(16)
	v_pk_fma_f32 v[62:63], v[62:63], v[102:103], v[118:119]
	v_pk_fma_f32 v[60:61], v[60:61], v[100:101], v[116:117]
	v_bfe_u32 v92, v60, 16, 1
	v_bfe_u32 v93, v61, 16, 1
	v_bfe_u32 v94, v62, 16, 1
	v_bfe_u32 v95, v63, 16, 1
	v_add3_u32 v60, v60, v92, s19
	v_add3_u32 v61, v61, v93, s19
	v_add3_u32 v62, v62, v94, s19
	v_add3_u32 v63, v63, v95, s19
	v_lshrrev_b32_e32 v60, 16, v60
	v_lshrrev_b32_e32 v62, 16, v62
	v_and_or_b32 v60, v61, s20, v60
	v_and_or_b32 v61, v63, s20, v62
	global_store_dwordx2 v1, v[60:61], s[0:1]
	v_pk_fma_f32 v[66:67], v[66:67], v[106:107], v[122:123]
	v_pk_fma_f32 v[64:65], v[64:65], v[104:105], v[120:121]
	v_bfe_u32 v92, v64, 16, 1
	v_bfe_u32 v93, v65, 16, 1
	v_bfe_u32 v94, v66, 16, 1
	v_bfe_u32 v95, v67, 16, 1
	v_add3_u32 v64, v64, v92, s19
	v_add3_u32 v65, v65, v93, s19
	v_add3_u32 v66, v66, v94, s19
	v_add3_u32 v67, v67, v95, s19
	v_lshrrev_b32_e32 v64, 16, v64
	v_lshrrev_b32_e32 v66, 16, v66
	v_and_or_b32 v64, v65, s20, v64
	v_and_or_b32 v65, v67, s20, v66
	global_store_dwordx2 v1, v[64:65], s[0:1] offset:512
	v_pk_fma_f32 v[70:71], v[70:71], v[110:111], v[126:127]
	v_pk_fma_f32 v[68:69], v[68:69], v[108:109], v[124:125]
	v_bfe_u32 v92, v68, 16, 1
	v_bfe_u32 v93, v69, 16, 1
	v_bfe_u32 v94, v70, 16, 1
	v_bfe_u32 v95, v71, 16, 1
	v_add3_u32 v68, v68, v92, s19
	v_add3_u32 v69, v69, v93, s19
	v_add3_u32 v70, v70, v94, s19
	v_add3_u32 v71, v71, v95, s19
	v_lshrrev_b32_e32 v68, 16, v68
	v_lshrrev_b32_e32 v70, 16, v70
	v_and_or_b32 v68, v69, s20, v68
	v_and_or_b32 v69, v71, s20, v70
	global_store_dwordx2 v1, v[68:69], s[0:1] offset:1024
	v_pk_fma_f32 v[74:75], v[74:75], v[114:115], v[130:131]
	v_pk_fma_f32 v[72:73], v[72:73], v[112:113], v[128:129]
	v_bfe_u32 v92, v72, 16, 1
	v_bfe_u32 v93, v73, 16, 1
	v_bfe_u32 v94, v74, 16, 1
	v_bfe_u32 v95, v75, 16, 1
	v_add3_u32 v72, v72, v92, s19
	v_add3_u32 v73, v73, v93, s19
	v_add3_u32 v74, v74, v94, s19
	v_add3_u32 v75, v75, v95, s19
	v_lshrrev_b32_e32 v72, 16, v72
	v_lshrrev_b32_e32 v74, 16, v74
	v_and_or_b32 v72, v73, s20, v72
	v_and_or_b32 v73, v75, s20, v74
	global_store_dwordx2 v1, v[72:73], s[0:1] offset:1536
	v_pk_fma_f32 v[78:79], v[78:79], v[102:103], v[118:119]
	v_pk_fma_f32 v[76:77], v[76:77], v[100:101], v[116:117]
	v_bfe_u32 v92, v76, 16, 1
	v_bfe_u32 v93, v77, 16, 1
	v_bfe_u32 v94, v78, 16, 1
	v_bfe_u32 v95, v79, 16, 1
	v_add3_u32 v76, v76, v92, s19
	v_add3_u32 v77, v77, v93, s19
	v_add3_u32 v78, v78, v94, s19
	v_add3_u32 v79, v79, v95, s19
	v_lshrrev_b32_e32 v76, 16, v76
	v_lshrrev_b32_e32 v78, 16, v78
	v_and_or_b32 v76, v77, s20, v76
	v_and_or_b32 v77, v79, s20, v78
	global_store_dwordx2 v1, v[76:77], s[0:1] offset:2048
	v_pk_fma_f32 v[82:83], v[82:83], v[106:107], v[122:123]
	v_pk_fma_f32 v[80:81], v[80:81], v[104:105], v[120:121]
	v_bfe_u32 v92, v80, 16, 1
	v_bfe_u32 v93, v81, 16, 1
	v_bfe_u32 v94, v82, 16, 1
	v_bfe_u32 v95, v83, 16, 1
	v_add3_u32 v80, v80, v92, s19
	v_add3_u32 v81, v81, v93, s19
	v_add3_u32 v82, v82, v94, s19
	v_add3_u32 v83, v83, v95, s19
	v_lshrrev_b32_e32 v80, 16, v80
	v_lshrrev_b32_e32 v82, 16, v82
	v_and_or_b32 v80, v81, s20, v80
	v_and_or_b32 v81, v83, s20, v82
	global_store_dwordx2 v1, v[80:81], s[0:1] offset:2560
	v_pk_fma_f32 v[86:87], v[86:87], v[110:111], v[126:127]
	v_pk_fma_f32 v[84:85], v[84:85], v[108:109], v[124:125]
	v_bfe_u32 v92, v84, 16, 1
	v_bfe_u32 v93, v85, 16, 1
	v_bfe_u32 v94, v86, 16, 1
	v_bfe_u32 v95, v87, 16, 1
	v_add3_u32 v84, v84, v92, s19
	v_add3_u32 v85, v85, v93, s19
	v_add3_u32 v86, v86, v94, s19
	v_add3_u32 v87, v87, v95, s19
	v_lshrrev_b32_e32 v84, 16, v84
	v_lshrrev_b32_e32 v86, 16, v86
	v_and_or_b32 v84, v85, s20, v84
	v_and_or_b32 v85, v87, s20, v86
	global_store_dwordx2 v1, v[84:85], s[0:1] offset:3072
	v_pk_fma_f32 v[90:91], v[90:91], v[114:115], v[130:131]
	v_pk_fma_f32 v[88:89], v[88:89], v[112:113], v[128:129]
	v_bfe_u32 v92, v88, 16, 1
	v_bfe_u32 v93, v89, 16, 1
	v_bfe_u32 v94, v90, 16, 1
	v_bfe_u32 v95, v91, 16, 1
	v_add3_u32 v88, v88, v92, s19
	v_add3_u32 v89, v89, v93, s19
	v_add3_u32 v90, v90, v94, s19
	v_add3_u32 v91, v91, v95, s19
	v_lshrrev_b32_e32 v88, 16, v88
	v_lshrrev_b32_e32 v90, 16, v90
	v_and_or_b32 v88, v89, s20, v88
	v_and_or_b32 v89, v91, s20, v90
	global_store_dwordx2 v1, v[88:89], s[0:1] offset:3584
	s_add_u32 s0, s0, 0x1000
	s_addc_u32 s1, s1, 0
	global_load_dwordx4 v[60:63], v[14:15], off offset:-4096
	global_load_dwordx4 v[64:67], v[14:15], off offset:-3072
	global_load_dwordx4 v[68:71], v[14:15], off offset:-2048
	global_load_dwordx4 v[72:75], v[14:15], off offset:-1024
	global_load_dwordx4 v[76:79], v[14:15], off
	global_load_dwordx4 v[80:83], v[14:15], off offset:1024
	global_load_dwordx4 v[84:87], v[14:15], off offset:2048
	global_load_dwordx4 v[88:91], v[14:15], off offset:3072
	v_lshl_add_u64 v[14:15], v[14:15], 0, s[12:13]
	s_waitcnt vmcnt(16)
	v_pk_fma_f32 v[18:19], v[18:19], v[102:103], v[118:119]
	v_pk_fma_f32 v[16:17], v[16:17], v[100:101], v[116:117]
	v_bfe_u32 v92, v16, 16, 1
	v_bfe_u32 v93, v17, 16, 1
	v_bfe_u32 v94, v18, 16, 1
	v_bfe_u32 v95, v19, 16, 1
	v_add3_u32 v16, v16, v92, s19
	v_add3_u32 v17, v17, v93, s19
	v_add3_u32 v18, v18, v94, s19
	v_add3_u32 v19, v19, v95, s19
	v_lshrrev_b32_e32 v16, 16, v16
	v_lshrrev_b32_e32 v18, 16, v18
	v_and_or_b32 v16, v17, s20, v16
	v_and_or_b32 v17, v19, s20, v18
	global_store_dwordx2 v1, v[16:17], s[0:1]
	v_pk_fma_f32 v[22:23], v[22:23], v[106:107], v[122:123]
	v_pk_fma_f32 v[20:21], v[20:21], v[104:105], v[120:121]
	v_bfe_u32 v92, v20, 16, 1
	v_bfe_u32 v93, v21, 16, 1
	v_bfe_u32 v94, v22, 16, 1
	v_bfe_u32 v95, v23, 16, 1
	v_add3_u32 v20, v20, v92, s19
	v_add3_u32 v21, v21, v93, s19
	v_add3_u32 v22, v22, v94, s19
	v_add3_u32 v23, v23, v95, s19
	v_lshrrev_b32_e32 v20, 16, v20
	v_lshrrev_b32_e32 v22, 16, v22
	v_and_or_b32 v20, v21, s20, v20
	v_and_or_b32 v21, v23, s20, v22
	global_store_dwordx2 v1, v[20:21], s[0:1] offset:512
	v_pk_fma_f32 v[26:27], v[26:27], v[110:111], v[126:127]
	v_pk_fma_f32 v[24:25], v[24:25], v[108:109], v[124:125]
	v_bfe_u32 v92, v24, 16, 1
	v_bfe_u32 v93, v25, 16, 1
	v_bfe_u32 v94, v26, 16, 1
	v_bfe_u32 v95, v27, 16, 1
	v_add3_u32 v24, v24, v92, s19
	v_add3_u32 v25, v25, v93, s19
	v_add3_u32 v26, v26, v94, s19
	v_add3_u32 v27, v27, v95, s19
	v_lshrrev_b32_e32 v24, 16, v24
	v_lshrrev_b32_e32 v26, 16, v26
	v_and_or_b32 v24, v25, s20, v24
	v_and_or_b32 v25, v27, s20, v26
	global_store_dwordx2 v1, v[24:25], s[0:1] offset:1024
	v_pk_fma_f32 v[30:31], v[30:31], v[114:115], v[130:131]
	v_pk_fma_f32 v[28:29], v[28:29], v[112:113], v[128:129]
	v_bfe_u32 v92, v28, 16, 1
	v_bfe_u32 v93, v29, 16, 1
	v_bfe_u32 v94, v30, 16, 1
	v_bfe_u32 v95, v31, 16, 1
	v_add3_u32 v28, v28, v92, s19
	v_add3_u32 v29, v29, v93, s19
	v_add3_u32 v30, v30, v94, s19
	v_add3_u32 v31, v31, v95, s19
	v_lshrrev_b32_e32 v28, 16, v28
	v_lshrrev_b32_e32 v30, 16, v30
	v_and_or_b32 v28, v29, s20, v28
	v_and_or_b32 v29, v31, s20, v30
	global_store_dwordx2 v1, v[28:29], s[0:1] offset:1536
	v_pk_fma_f32 v[34:35], v[34:35], v[102:103], v[118:119]
	v_pk_fma_f32 v[32:33], v[32:33], v[100:101], v[116:117]
	v_bfe_u32 v92, v32, 16, 1
	v_bfe_u32 v93, v33, 16, 1
	v_bfe_u32 v94, v34, 16, 1
	v_bfe_u32 v95, v35, 16, 1
	v_add3_u32 v32, v32, v92, s19
	v_add3_u32 v33, v33, v93, s19
	v_add3_u32 v34, v34, v94, s19
	v_add3_u32 v35, v35, v95, s19
	v_lshrrev_b32_e32 v32, 16, v32
	v_lshrrev_b32_e32 v34, 16, v34
	v_and_or_b32 v32, v33, s20, v32
	v_and_or_b32 v33, v35, s20, v34
	global_store_dwordx2 v1, v[32:33], s[0:1] offset:2048
	v_pk_fma_f32 v[38:39], v[38:39], v[106:107], v[122:123]
	v_pk_fma_f32 v[36:37], v[36:37], v[104:105], v[120:121]
	v_bfe_u32 v92, v36, 16, 1
	v_bfe_u32 v93, v37, 16, 1
	v_bfe_u32 v94, v38, 16, 1
	v_bfe_u32 v95, v39, 16, 1
	v_add3_u32 v36, v36, v92, s19
	v_add3_u32 v37, v37, v93, s19
	v_add3_u32 v38, v38, v94, s19
	v_add3_u32 v39, v39, v95, s19
	v_lshrrev_b32_e32 v36, 16, v36
	v_lshrrev_b32_e32 v38, 16, v38
	v_and_or_b32 v36, v37, s20, v36
	v_and_or_b32 v37, v39, s20, v38
	global_store_dwordx2 v1, v[36:37], s[0:1] offset:2560
	v_pk_fma_f32 v[42:43], v[42:43], v[110:111], v[126:127]
	v_pk_fma_f32 v[40:41], v[40:41], v[108:109], v[124:125]
	v_bfe_u32 v92, v40, 16, 1
	v_bfe_u32 v93, v41, 16, 1
	v_bfe_u32 v94, v42, 16, 1
	v_bfe_u32 v95, v43, 16, 1
	v_add3_u32 v40, v40, v92, s19
	v_add3_u32 v41, v41, v93, s19
	v_add3_u32 v42, v42, v94, s19
	v_add3_u32 v43, v43, v95, s19
	v_lshrrev_b32_e32 v40, 16, v40
	v_lshrrev_b32_e32 v42, 16, v42
	v_and_or_b32 v40, v41, s20, v40
	v_and_or_b32 v41, v43, s20, v42
	global_store_dwordx2 v1, v[40:41], s[0:1] offset:3072
	v_pk_fma_f32 v[46:47], v[46:47], v[114:115], v[130:131]
	v_pk_fma_f32 v[44:45], v[44:45], v[112:113], v[128:129]
	v_bfe_u32 v92, v44, 16, 1
	v_bfe_u32 v93, v45, 16, 1
	v_bfe_u32 v94, v46, 16, 1
	v_bfe_u32 v95, v47, 16, 1
	v_add3_u32 v44, v44, v92, s19
	v_add3_u32 v45, v45, v93, s19
	v_add3_u32 v46, v46, v94, s19
	v_add3_u32 v47, v47, v95, s19
	v_lshrrev_b32_e32 v44, 16, v44
	v_lshrrev_b32_e32 v46, 16, v46
	v_and_or_b32 v44, v45, s20, v44
	v_and_or_b32 v45, v47, s20, v46
	global_store_dwordx2 v1, v[44:45], s[0:1] offset:3584
	s_add_u32 s0, s0, 0x1000
	s_addc_u32 s1, s1, 0
	s_waitcnt vmcnt(8)
	v_pk_fma_f32 v[62:63], v[62:63], v[102:103], v[118:119]
	v_pk_fma_f32 v[60:61], v[60:61], v[100:101], v[116:117]
	v_bfe_u32 v92, v60, 16, 1
	v_bfe_u32 v93, v61, 16, 1
	v_bfe_u32 v94, v62, 16, 1
	v_bfe_u32 v95, v63, 16, 1
	v_add3_u32 v60, v60, v92, s19
	v_add3_u32 v61, v61, v93, s19
	v_add3_u32 v62, v62, v94, s19
	v_add3_u32 v63, v63, v95, s19
	v_lshrrev_b32_e32 v60, 16, v60
	v_lshrrev_b32_e32 v62, 16, v62
	v_and_or_b32 v60, v61, s20, v60
	v_and_or_b32 v61, v63, s20, v62
	global_store_dwordx2 v1, v[60:61], s[0:1]
	v_pk_fma_f32 v[66:67], v[66:67], v[106:107], v[122:123]
	v_pk_fma_f32 v[64:65], v[64:65], v[104:105], v[120:121]
	v_bfe_u32 v92, v64, 16, 1
	v_bfe_u32 v93, v65, 16, 1
	v_bfe_u32 v94, v66, 16, 1
	v_bfe_u32 v95, v67, 16, 1
	v_add3_u32 v64, v64, v92, s19
	v_add3_u32 v65, v65, v93, s19
	v_add3_u32 v66, v66, v94, s19
	v_add3_u32 v67, v67, v95, s19
	v_lshrrev_b32_e32 v64, 16, v64
	v_lshrrev_b32_e32 v66, 16, v66
	v_and_or_b32 v64, v65, s20, v64
	v_and_or_b32 v65, v67, s20, v66
	global_store_dwordx2 v1, v[64:65], s[0:1] offset:512
	v_pk_fma_f32 v[70:71], v[70:71], v[110:111], v[126:127]
	v_pk_fma_f32 v[68:69], v[68:69], v[108:109], v[124:125]
	v_bfe_u32 v92, v68, 16, 1
	v_bfe_u32 v93, v69, 16, 1
	v_bfe_u32 v94, v70, 16, 1
	v_bfe_u32 v95, v71, 16, 1
	v_add3_u32 v68, v68, v92, s19
	v_add3_u32 v69, v69, v93, s19
	v_add3_u32 v70, v70, v94, s19
	v_add3_u32 v71, v71, v95, s19
	v_lshrrev_b32_e32 v68, 16, v68
	v_lshrrev_b32_e32 v70, 16, v70
	v_and_or_b32 v68, v69, s20, v68
	v_and_or_b32 v69, v71, s20, v70
	global_store_dwordx2 v1, v[68:69], s[0:1] offset:1024
	v_pk_fma_f32 v[74:75], v[74:75], v[114:115], v[130:131]
	v_pk_fma_f32 v[72:73], v[72:73], v[112:113], v[128:129]
	v_bfe_u32 v92, v72, 16, 1
	v_bfe_u32 v93, v73, 16, 1
	v_bfe_u32 v94, v74, 16, 1
	v_bfe_u32 v95, v75, 16, 1
	v_add3_u32 v72, v72, v92, s19
	v_add3_u32 v73, v73, v93, s19
	v_add3_u32 v74, v74, v94, s19
	v_add3_u32 v75, v75, v95, s19
	v_lshrrev_b32_e32 v72, 16, v72
	v_lshrrev_b32_e32 v74, 16, v74
	v_and_or_b32 v72, v73, s20, v72
	v_and_or_b32 v73, v75, s20, v74
	global_store_dwordx2 v1, v[72:73], s[0:1] offset:1536
	v_pk_fma_f32 v[78:79], v[78:79], v[102:103], v[118:119]
	v_pk_fma_f32 v[76:77], v[76:77], v[100:101], v[116:117]
	v_bfe_u32 v92, v76, 16, 1
	v_bfe_u32 v93, v77, 16, 1
	v_bfe_u32 v94, v78, 16, 1
	v_bfe_u32 v95, v79, 16, 1
	v_add3_u32 v76, v76, v92, s19
	v_add3_u32 v77, v77, v93, s19
	v_add3_u32 v78, v78, v94, s19
	v_add3_u32 v79, v79, v95, s19
	v_lshrrev_b32_e32 v76, 16, v76
	v_lshrrev_b32_e32 v78, 16, v78
	v_and_or_b32 v76, v77, s20, v76
	v_and_or_b32 v77, v79, s20, v78
	global_store_dwordx2 v1, v[76:77], s[0:1] offset:2048
	v_pk_fma_f32 v[82:83], v[82:83], v[106:107], v[122:123]
	v_pk_fma_f32 v[80:81], v[80:81], v[104:105], v[120:121]
	v_bfe_u32 v92, v80, 16, 1
	v_bfe_u32 v93, v81, 16, 1
	v_bfe_u32 v94, v82, 16, 1
	v_bfe_u32 v95, v83, 16, 1
	v_add3_u32 v80, v80, v92, s19
	v_add3_u32 v81, v81, v93, s19
	v_add3_u32 v82, v82, v94, s19
	v_add3_u32 v83, v83, v95, s19
	v_lshrrev_b32_e32 v80, 16, v80
	v_lshrrev_b32_e32 v82, 16, v82
	v_and_or_b32 v80, v81, s20, v80
	v_and_or_b32 v81, v83, s20, v82
	global_store_dwordx2 v1, v[80:81], s[0:1] offset:2560
	v_pk_fma_f32 v[86:87], v[86:87], v[110:111], v[126:127]
	v_pk_fma_f32 v[84:85], v[84:85], v[108:109], v[124:125]
	v_bfe_u32 v92, v84, 16, 1
	v_bfe_u32 v93, v85, 16, 1
	v_bfe_u32 v94, v86, 16, 1
	v_bfe_u32 v95, v87, 16, 1
	v_add3_u32 v84, v84, v92, s19
	v_add3_u32 v85, v85, v93, s19
	v_add3_u32 v86, v86, v94, s19
	v_add3_u32 v87, v87, v95, s19
	v_lshrrev_b32_e32 v84, 16, v84
	v_lshrrev_b32_e32 v86, 16, v86
	v_and_or_b32 v84, v85, s20, v84
	v_and_or_b32 v85, v87, s20, v86
	global_store_dwordx2 v1, v[84:85], s[0:1] offset:3072
	v_pk_fma_f32 v[90:91], v[90:91], v[114:115], v[130:131]
	v_pk_fma_f32 v[88:89], v[88:89], v[112:113], v[128:129]
	v_bfe_u32 v92, v88, 16, 1
	v_bfe_u32 v93, v89, 16, 1
	v_bfe_u32 v94, v90, 16, 1
	v_bfe_u32 v95, v91, 16, 1
	v_add3_u32 v88, v88, v92, s19
	v_add3_u32 v89, v89, v93, s19
	v_add3_u32 v90, v90, v94, s19
	v_add3_u32 v91, v91, v95, s19
	v_lshrrev_b32_e32 v88, 16, v88
	v_lshrrev_b32_e32 v90, 16, v90
	v_and_or_b32 v88, v89, s20, v88
	v_and_or_b32 v89, v91, s20, v90
	global_store_dwordx2 v1, v[88:89], s[0:1] offset:3584
	s_add_u32 s0, s0, 0x1000
	s_addc_u32 s1, s1, 0
